# attention: unpacked pk f32 + canonicalizing v_max removed (85 sites), MFMA-result pads re-derived; no LDS hoist
# speedup vs baseline: 1.0110x; 1.0110x over previous
.LBB0_1055:
	v_add3_u32 v83, s18, v186, v188
	ds_read_b128 v[84:87], v83
	ds_read_b128 v[92:95], v83 offset:64
	s_waitcnt lgkmcnt(1)
	v_mfma_f32_16x16x32_bf16 v[88:91], v[84:87], v[0:3], 0
	ds_read_b128 v[98:101], v83 offset:3392
	ds_read_b128 v[102:105], v83 offset:6720
	ds_read_b128 v[156:159], v83 offset:10048
	v_mfma_f32_16x16x32_bf16 v[84:87], v[84:87], v[12:15], 0
	s_waitcnt lgkmcnt(3)
	v_mfma_f32_16x16x32_bf16 v[88:91], v[92:95], v[4:7], v[88:91]
	v_mfma_f32_16x16x32_bf16 v[84:87], v[92:95], v[16:19], v[84:87]
	ds_read_b128 v[92:95], v83 offset:128
	s_waitcnt lgkmcnt(0)
	v_mfma_f32_16x16x32_bf16 v[160:163], v[92:95], v[8:11], v[88:91]
	v_mfma_f32_16x16x32_bf16 v[90:93], v[92:95], v[20:23], v[84:87]
	s_nop 3
	ds_read_b128 v[84:87], v83 offset:3328
	s_waitcnt lgkmcnt(0)
	v_mfma_f32_16x16x32_bf16 v[94:97], v[84:87], v[0:3], 0
	s_nop 0
	v_mfma_f32_16x16x32_bf16 v[84:87], v[84:87], v[12:15], 0
	v_mfma_f32_16x16x32_bf16 v[94:97], v[98:101], v[4:7], v[94:97]
	v_mfma_f32_16x16x32_bf16 v[84:87], v[98:101], v[16:19], v[84:87]
	ds_read_b128 v[98:101], v83 offset:3456
	s_waitcnt lgkmcnt(0)
	v_mfma_f32_16x16x32_bf16 v[166:169], v[98:101], v[8:11], v[94:97]
	v_mfma_f32_16x16x32_bf16 v[94:97], v[98:101], v[20:23], v[84:87]
	s_nop 3
	ds_read_b128 v[84:87], v83 offset:6656
	s_waitcnt lgkmcnt(0)
	v_mfma_f32_16x16x32_bf16 v[98:101], v[84:87], v[0:3], 0
	v_mfma_f32_16x16x32_bf16 v[84:87], v[84:87], v[12:15], 0
	v_mfma_f32_16x16x32_bf16 v[98:101], v[102:105], v[4:7], v[98:101]
	v_mfma_f32_16x16x32_bf16 v[84:87], v[102:105], v[16:19], v[84:87]
	ds_read_b128 v[102:105], v83 offset:6784
	s_waitcnt lgkmcnt(0)
	v_mfma_f32_16x16x32_bf16 v[174:177], v[102:105], v[8:11], v[98:101]
	v_mfma_f32_16x16x32_bf16 v[98:101], v[102:105], v[20:23], v[84:87]
	s_nop 3
	ds_read_b128 v[84:87], v83 offset:9984
	s_waitcnt lgkmcnt(0)
	v_mfma_f32_16x16x32_bf16 v[102:105], v[84:87], v[0:3], 0
	v_mfma_f32_16x16x32_bf16 v[84:87], v[84:87], v[12:15], 0
	v_mfma_f32_16x16x32_bf16 v[102:105], v[156:159], v[4:7], v[102:105]
	v_mfma_f32_16x16x32_bf16 v[84:87], v[156:159], v[16:19], v[84:87]
	ds_read_b128 v[156:159], v83 offset:10112
	s_waitcnt lgkmcnt(0)
	v_mfma_f32_16x16x32_bf16 v[192:195], v[156:159], v[8:11], v[102:105]
	v_mfma_f32_16x16x32_bf16 v[102:105], v[156:159], v[20:23], v[84:87]
	v_max_f32_e32 v153, v90, v91
	v_max_f32_e32 v83, v160, v161
	s_nop 1
	v_max_f32_e32 v84, v162, v163
	v_max_f32_e32 v85, v168, v169
	v_max3_f32 v85, v166, v167, v85
	v_max3_f32 v83, v83, v84, v85
	v_max_f32_e32 v84, v176, v177
	v_max_f32_e32 v86, v194, v194
	v_max_f32_e32 v85, v86, v195
	v_max3_f32 v84, v174, v175, v84
	v_max3_f32 v85, v192, v193, v85
	v_max3_f32 v83, v83, v84, v85
	s_waitcnt lgkmcnt(0)
	v_mov_b32_e32 v84, v83
	s_nop 1
	v_permlane16_swap_b32_e32 v83, v84
	v_max_f32_e32 v83, v83, v84
	v_mov_b32_e32 v84, v83
	s_nop 1
	v_permlane32_swap_b32_e32 v83, v84
	v_max3_f32 v143, v82, v83, v84
	v_sub_f32_e32 v82, v82, v143
	v_exp_f32_e32 v158, v82
	v_sub_f32_e32 v82, v160, v143
	v_exp_f32_e32 v152, v82
	v_sub_f32_e32 v82, v161, v143
	v_exp_f32_e32 v156, v82
	v_sub_f32_e32 v82, v162, v143
	v_exp_f32_e32 v160, v82
	v_sub_f32_e32 v82, v163, v143
	v_exp_f32_e32 v162, v82
	v_sub_f32_e32 v82, v166, v143
	v_exp_f32_e32 v164, v82
	v_sub_f32_e32 v82, v167, v143
	v_exp_f32_e32 v166, v82
	v_sub_f32_e32 v82, v168, v143
	v_exp_f32_e32 v168, v82
	v_sub_f32_e32 v82, v169, v143
	v_exp_f32_e32 v170, v82
	v_sub_f32_e32 v82, v174, v143
	v_exp_f32_e32 v172, v82
	v_sub_f32_e32 v82, v175, v143
	v_exp_f32_e32 v174, v82
	v_sub_f32_e32 v82, v176, v143
	v_exp_f32_e32 v176, v82
	v_sub_f32_e32 v82, v177, v143
	v_exp_f32_e32 v178, v82
	v_sub_f32_e32 v82, v192, v143
	v_exp_f32_e32 v180, v82
	v_sub_f32_e32 v82, v193, v143
	v_exp_f32_e32 v182, v82
	v_sub_f32_e32 v82, v194, v143
	v_exp_f32_e32 v192, v82
	v_sub_f32_e32 v82, v195, v143
	v_exp_f32_e32 v194, v82
	v_mul_f32_e32 v84, v68, v158
	v_mul_f32_e32 v85, v69, v158
	v_mul_f32_e32 v82, v66, v158
	v_mul_f32_e32 v83, v67, v158
	v_mul_f32_e32 v88, v72, v158
	v_mul_f32_e32 v89, v73, v158
	v_mul_f32_e32 v86, v70, v158
	v_mul_f32_e32 v87, v71, v158
	v_mul_f32_e32 v76, v76, v158
	v_mul_f32_e32 v77, v77, v158
	v_mul_f32_e32 v74, v74, v158
	v_mul_f32_e32 v75, v75, v158
	v_mul_f32_e32 v68, v80, v158
	v_mul_f32_e32 v69, v81, v158
	v_mul_f32_e32 v66, v78, v158
	v_mul_f32_e32 v67, v79, v158
	v_max_f32_e32 v157, v92, v93
	v_max_f32_e32 v159, v96, v97
	v_max3_f32 v159, v94, v95, v159
	v_max3_f32 v153, v153, v157, v159
	v_max_f32_e32 v157, v100, v101
	v_max_f32_e32 v159, v104, v105
	v_max3_f32 v157, v98, v99, v157
	v_max3_f32 v159, v102, v103, v159
	v_max3_f32 v153, v153, v157, v159
	v_cvt_pk_bf16_f32 v70, v152, v156
	v_cvt_pk_bf16_f32 v71, v160, v162
	v_cvt_pk_bf16_f32 v72, v164, v166
	v_cvt_pk_bf16_f32 v73, v168, v170
	s_waitcnt lgkmcnt(0)
	v_mov_b32_e32 v157, v153
	s_nop 1
	v_permlane16_swap_b32_e32 v153, v157
	v_max_f32_e32 v153, v153, v157
	v_mov_b32_e32 v157, v153
	s_nop 1
	v_permlane32_swap_b32_e32 v153, v157
	v_max3_f32 v191, v127, v153, v157
	v_sub_f32_e32 v90, v90, v191
	v_exp_f32_e32 v153, v90
	v_sub_f32_e32 v90, v91, v191
	v_exp_f32_e32 v157, v90
	v_sub_f32_e32 v90, v92, v191
	v_exp_f32_e32 v161, v90
	v_sub_f32_e32 v90, v93, v191
	v_exp_f32_e32 v163, v90
	v_sub_f32_e32 v90, v94, v191
	v_exp_f32_e32 v165, v90
	v_sub_f32_e32 v90, v95, v191
	v_exp_f32_e32 v167, v90
	v_add_f32_e32 v90, 0, v152
	v_add_f32_e32 v91, 0, v153
	v_sub_f32_e32 v92, v96, v191
	v_add_f32_e32 v90, v156, v90
	v_add_f32_e32 v91, v157, v91
	v_exp_f32_e32 v169, v92
	v_add_f32_e32 v90, v160, v90
	v_add_f32_e32 v91, v161, v91
	v_sub_f32_e32 v92, v97, v191
	v_add_f32_e32 v90, v162, v90
	v_add_f32_e32 v91, v163, v91
	v_exp_f32_e32 v171, v92
	v_sub_f32_e32 v92, v98, v191
	v_add_f32_e32 v90, v164, v90
	v_add_f32_e32 v91, v165, v91
	v_exp_f32_e32 v173, v92
	v_sub_f32_e32 v92, v99, v191
	v_add_f32_e32 v90, v166, v90
	v_add_f32_e32 v91, v167, v91
	v_exp_f32_e32 v175, v92
	v_sub_f32_e32 v92, v100, v191
	v_exp_f32_e32 v177, v92
	v_sub_f32_e32 v92, v101, v191
	v_add_f32_e32 v90, v168, v90
	v_add_f32_e32 v91, v169, v91
	v_exp_f32_e32 v179, v92
	v_sub_f32_e32 v92, v102, v191
	v_add_f32_e32 v90, v170, v90
	v_add_f32_e32 v91, v171, v91
	v_exp_f32_e32 v181, v92
	v_sub_f32_e32 v92, v103, v191
	v_add_f32_e32 v90, v172, v90
	v_add_f32_e32 v91, v173, v91
	v_exp_f32_e32 v183, v92
	v_sub_f32_e32 v92, v104, v191
	v_add_f32_e32 v90, v174, v90
	v_add_f32_e32 v91, v175, v91
	v_sub_f32_e32 v127, v127, v191
	v_exp_f32_e32 v193, v92
	v_sub_f32_e32 v92, v105, v191
	v_add_f32_e32 v90, v176, v90
	v_add_f32_e32 v91, v177, v91
	v_exp_f32_e32 v159, v127
	v_exp_f32_e32 v195, v92
	v_add_f32_e32 v90, v178, v90
	v_add_f32_e32 v91, v179, v91
	v_cvt_pk_bf16_f32 v78, v172, v174
	v_add_f32_e32 v90, v180, v90
	v_add_f32_e32 v91, v181, v91
	v_mov_b32_e32 v98, v159
	v_add_f32_e32 v90, v182, v90
	v_add_f32_e32 v91, v183, v91
	v_mul_f32_e32 v92, v52, v98
	v_mul_f32_e32 v93, v53, v98
	v_add_f32_e32 v90, v192, v90
	v_add_f32_e32 v91, v193, v91
	v_mul_f32_e32 v96, v56, v98
	v_mul_f32_e32 v97, v57, v98
	v_add_f32_e32 v90, v194, v90
	v_add_f32_e32 v91, v195, v91
	v_mul_f32_e32 v94, v54, v98
	v_mul_f32_e32 v95, v55, v98
	v_pk_fma_f32 v[150:151], v[150:151], v[158:159], v[90:91]
	v_mul_f32_e32 v90, v50, v98
	v_mul_f32_e32 v91, v51, v98
	v_mul_f32_e32 v60, v60, v98
	v_mul_f32_e32 v61, v61, v98
	v_mul_f32_e32 v58, v58, v98
	v_mul_f32_e32 v59, v59, v98
	v_mul_f32_e32 v52, v64, v98
	v_mul_f32_e32 v53, v65, v98
	v_mul_f32_e32 v50, v62, v98
	v_mul_f32_e32 v51, v63, v98
	v_lshlrev_b32_e32 v98, 1, v187
	v_add3_u32 v127, s18, v98, v189
	ds_read_b64_tr_b16 v[100:101], v127 offset:15872
	ds_read_b64_tr_b16 v[98:99], v127 offset:13312
	ds_read_b64_tr_b16 v[102:103], v127 offset:13320
	v_cvt_pk_bf16_f32 v54, v153, v157
	v_cvt_pk_bf16_f32 v55, v161, v163
	v_cvt_pk_bf16_f32 v56, v165, v167
	v_cvt_pk_bf16_f32 v57, v169, v171
	s_waitcnt lgkmcnt(1)
	v_mfma_f32_16x16x32_bf16 v[82:85], v[98:101], v[70:73], v[82:85]
	ds_read_b64_tr_b16 v[104:105], v127 offset:15880
	v_cvt_pk_bf16_f32 v79, v176, v178
	v_cvt_pk_bf16_f32 v80, v180, v182
	v_mfma_f32_16x16x32_bf16 v[90:93], v[98:101], v[54:57], v[90:93]
	ds_read_b64_tr_b16 v[98:99], v127 offset:13376
	ds_read_b64_tr_b16 v[100:101], v127 offset:15936
	v_cvt_pk_bf16_f32 v81, v192, v194
	v_cvt_pk_bf16_f32 v62, v173, v175
	s_waitcnt lgkmcnt(0)
	v_mfma_f32_16x16x32_bf16 v[74:77], v[98:101], v[70:73], v[74:77]
	v_cvt_pk_bf16_f32 v63, v177, v179
	v_cvt_pk_bf16_f32 v64, v181, v183
	v_cvt_pk_bf16_f32 v65, v193, v195
	v_mfma_f32_16x16x32_bf16 v[58:61], v[98:101], v[54:57], v[58:61]
	ds_read_b64_tr_b16 v[98:99], v127 offset:13384
	ds_read_b64_tr_b16 v[100:101], v127 offset:15944
	v_mfma_f32_16x16x32_bf16 v[86:89], v[102:105], v[70:73], v[86:89]
	v_mfma_f32_16x16x32_bf16 v[94:97], v[102:105], v[54:57], v[94:97]
	s_waitcnt lgkmcnt(0)
	v_mfma_f32_16x16x32_bf16 v[102:105], v[98:101], v[70:73], v[66:69]
	v_mfma_f32_16x16x32_bf16 v[98:101], v[98:101], v[54:57], v[50:53]
	s_nop 2
	ds_read_b64_tr_b16 v[50:51], v127 offset:18432
	ds_read_b64_tr_b16 v[52:53], v127 offset:20992
	ds_read_b64_tr_b16 v[54:55], v127 offset:18440
	ds_read_b64_tr_b16 v[56:57], v127 offset:21000
	s_waitcnt lgkmcnt(2)
	v_mfma_f32_16x16x32_bf16 v[66:69], v[50:53], v[78:81], v[82:85]
	s_nop 2
	ds_read_b64_tr_b16 v[82:83], v127 offset:18496
	ds_read_b64_tr_b16 v[84:85], v127 offset:21056
	s_waitcnt lgkmcnt(0)
	v_mfma_f32_16x16x32_bf16 v[74:77], v[82:85], v[78:81], v[74:77]
	v_mfma_f32_16x16x32_bf16 v[58:61], v[82:85], v[62:65], v[58:61]
	ds_read_b64_tr_b16 v[82:83], v127 offset:18504
	ds_read_b64_tr_b16 v[84:85], v127 offset:21064
	v_mov_b32_e32 v127, v191
	v_mfma_f32_16x16x32_bf16 v[50:53], v[50:53], v[62:65], v[90:93]
	v_mfma_f32_16x16x32_bf16 v[70:73], v[54:57], v[78:81], v[86:89]
	v_mfma_f32_16x16x32_bf16 v[54:57], v[54:57], v[62:65], v[94:97]
	s_waitcnt lgkmcnt(0)
	v_mfma_f32_16x16x32_bf16 v[78:81], v[82:85], v[78:81], v[102:105]
	v_mfma_f32_16x16x32_bf16 v[62:65], v[82:85], v[62:65], v[98:101]
	v_mov_b32_e32 v82, v143
	s_add_i32 s6, s48, -2
	s_cmp_ge_i32 s6, s47
	s_cbranch_scc1 .LBB0_1042
.LBB0_1056:
	s_and_b32 s6, s6, 3
	s_mulk_i32 s6, 0x5c00
	s_add_i32 s18, s6, 0
	v_add3_u32 v83, s18, v186, v188
	ds_read_b128 v[84:87], v83
	ds_read_b128 v[92:95], v83 offset:64
	s_waitcnt lgkmcnt(1)
	v_mfma_f32_16x16x32_bf16 v[88:91], v[84:87], v[0:3], 0
	ds_read_b128 v[98:101], v83 offset:3392
	ds_read_b128 v[102:105], v83 offset:6720
	ds_read_b128 v[156:159], v83 offset:10048
	v_mfma_f32_16x16x32_bf16 v[84:87], v[84:87], v[12:15], 0
	s_waitcnt lgkmcnt(3)
	v_mfma_f32_16x16x32_bf16 v[88:91], v[92:95], v[4:7], v[88:91]
	v_mfma_f32_16x16x32_bf16 v[84:87], v[92:95], v[16:19], v[84:87]
	ds_read_b128 v[92:95], v83 offset:128
	s_waitcnt lgkmcnt(0)
	v_mfma_f32_16x16x32_bf16 v[160:163], v[92:95], v[8:11], v[88:91]
	v_mfma_f32_16x16x32_bf16 v[90:93], v[92:95], v[20:23], v[84:87]
	s_nop 3
	ds_read_b128 v[84:87], v83 offset:3328
	s_waitcnt lgkmcnt(0)
	v_mfma_f32_16x16x32_bf16 v[94:97], v[84:87], v[0:3], 0
	s_nop 0
	v_mfma_f32_16x16x32_bf16 v[84:87], v[84:87], v[12:15], 0
	v_mfma_f32_16x16x32_bf16 v[94:97], v[98:101], v[4:7], v[94:97]
	v_mfma_f32_16x16x32_bf16 v[84:87], v[98:101], v[16:19], v[84:87]
	ds_read_b128 v[98:101], v83 offset:3456
	s_waitcnt lgkmcnt(0)
	v_mfma_f32_16x16x32_bf16 v[166:169], v[98:101], v[8:11], v[94:97]
	v_mfma_f32_16x16x32_bf16 v[94:97], v[98:101], v[20:23], v[84:87]
	s_nop 3
	ds_read_b128 v[84:87], v83 offset:6656
	s_waitcnt lgkmcnt(0)
	v_mfma_f32_16x16x32_bf16 v[98:101], v[84:87], v[0:3], 0
	v_mfma_f32_16x16x32_bf16 v[84:87], v[84:87], v[12:15], 0
	v_mfma_f32_16x16x32_bf16 v[98:101], v[102:105], v[4:7], v[98:101]
	v_mfma_f32_16x16x32_bf16 v[84:87], v[102:105], v[16:19], v[84:87]
	ds_read_b128 v[102:105], v83 offset:6784
	s_waitcnt lgkmcnt(0)
	v_mfma_f32_16x16x32_bf16 v[174:177], v[102:105], v[8:11], v[98:101]
	v_mfma_f32_16x16x32_bf16 v[98:101], v[102:105], v[20:23], v[84:87]
	s_nop 3
	ds_read_b128 v[84:87], v83 offset:9984
	s_waitcnt lgkmcnt(0)
	v_mfma_f32_16x16x32_bf16 v[102:105], v[84:87], v[0:3], 0
	v_mfma_f32_16x16x32_bf16 v[84:87], v[84:87], v[12:15], 0
	v_mfma_f32_16x16x32_bf16 v[102:105], v[156:159], v[4:7], v[102:105]
	v_mfma_f32_16x16x32_bf16 v[84:87], v[156:159], v[16:19], v[84:87]
	ds_read_b128 v[156:159], v83 offset:10112
	s_waitcnt lgkmcnt(0)
	v_mfma_f32_16x16x32_bf16 v[180:183], v[156:159], v[8:11], v[102:105]
	v_mfma_f32_16x16x32_bf16 v[102:105], v[156:159], v[20:23], v[84:87]
	v_max_f32_e32 v153, v90, v91
	v_max_f32_e32 v83, v160, v161
	s_nop 1
	v_max_f32_e32 v84, v162, v163
	v_max_f32_e32 v85, v168, v169
	v_max3_f32 v85, v166, v167, v85
	v_max3_f32 v83, v83, v84, v85
	v_max_f32_e32 v84, v176, v177
	v_max_f32_e32 v85, v182, v183
	v_max3_f32 v84, v174, v175, v84
	v_max3_f32 v85, v180, v181, v85
	v_max3_f32 v83, v83, v84, v85
	s_waitcnt lgkmcnt(0)
	v_mov_b32_e32 v84, v83
	s_nop 1
	v_permlane16_swap_b32_e32 v83, v84
	v_max_f32_e32 v83, v83, v84
	v_mov_b32_e32 v84, v83
	s_nop 1
	v_permlane32_swap_b32_e32 v83, v84
	v_max3_f32 v143, v82, v83, v84
	v_sub_f32_e32 v82, v82, v143
	v_exp_f32_e32 v158, v82
	v_sub_f32_e32 v82, v160, v143
	v_exp_f32_e32 v152, v82
	v_sub_f32_e32 v82, v161, v143
	v_exp_f32_e32 v156, v82
	v_sub_f32_e32 v82, v162, v143
	v_exp_f32_e32 v160, v82
	v_sub_f32_e32 v82, v163, v143
	v_exp_f32_e32 v162, v82
	v_sub_f32_e32 v82, v166, v143
	v_exp_f32_e32 v164, v82
	v_sub_f32_e32 v82, v167, v143
	v_exp_f32_e32 v166, v82
	v_sub_f32_e32 v82, v168, v143
	v_exp_f32_e32 v168, v82
	v_sub_f32_e32 v82, v169, v143
	v_exp_f32_e32 v170, v82
	v_sub_f32_e32 v82, v174, v143
	v_exp_f32_e32 v172, v82
	v_sub_f32_e32 v82, v175, v143
	v_exp_f32_e32 v174, v82
	v_sub_f32_e32 v82, v176, v143
	v_exp_f32_e32 v176, v82
	v_sub_f32_e32 v82, v177, v143
	v_exp_f32_e32 v178, v82
	v_sub_f32_e32 v82, v180, v143
	v_exp_f32_e32 v180, v82
	v_sub_f32_e32 v82, v181, v143
	v_exp_f32_e32 v192, v82
	v_sub_f32_e32 v82, v182, v143
	v_exp_f32_e32 v194, v82
	v_sub_f32_e32 v82, v183, v143
	v_exp_f32_e32 v196, v82
	v_mul_f32_e32 v84, v68, v158
	v_mul_f32_e32 v85, v69, v158
	v_mul_f32_e32 v82, v66, v158
	v_mul_f32_e32 v83, v67, v158
	v_mul_f32_e32 v88, v72, v158
	v_mul_f32_e32 v89, v73, v158
	v_mul_f32_e32 v86, v70, v158
	v_mul_f32_e32 v87, v71, v158
	v_mul_f32_e32 v76, v76, v158
	v_mul_f32_e32 v77, v77, v158
	v_mul_f32_e32 v74, v74, v158
	v_mul_f32_e32 v75, v75, v158
	v_mul_f32_e32 v68, v80, v158
	v_mul_f32_e32 v69, v81, v158
	v_mul_f32_e32 v66, v78, v158
	v_mul_f32_e32 v67, v79, v158
	v_max_f32_e32 v157, v92, v93
	v_max_f32_e32 v159, v96, v97
	v_max3_f32 v159, v94, v95, v159
	v_max3_f32 v153, v153, v157, v159
	v_max_f32_e32 v157, v100, v101
	v_max_f32_e32 v159, v104, v105
	v_max3_f32 v157, v98, v99, v157
	v_max3_f32 v159, v102, v103, v159
	v_max3_f32 v153, v153, v157, v159
	v_cvt_pk_bf16_f32 v70, v152, v156
	v_cvt_pk_bf16_f32 v71, v160, v162
	v_cvt_pk_bf16_f32 v72, v164, v166
	v_cvt_pk_bf16_f32 v73, v168, v170
	s_waitcnt lgkmcnt(0)
	v_mov_b32_e32 v157, v153
	s_nop 1
	v_permlane16_swap_b32_e32 v153, v157
	v_max_f32_e32 v153, v153, v157
	v_mov_b32_e32 v157, v153
	s_nop 1
	v_permlane32_swap_b32_e32 v153, v157
	v_max3_f32 v182, v127, v153, v157
	v_sub_f32_e32 v90, v90, v182
	v_exp_f32_e32 v153, v90
	v_sub_f32_e32 v90, v91, v182
	v_exp_f32_e32 v157, v90
	v_sub_f32_e32 v90, v92, v182
	v_exp_f32_e32 v161, v90
	v_sub_f32_e32 v90, v93, v182
	v_exp_f32_e32 v163, v90
	v_sub_f32_e32 v90, v94, v182
	v_exp_f32_e32 v165, v90
	v_sub_f32_e32 v90, v95, v182
	v_exp_f32_e32 v167, v90
	v_add_f32_e32 v90, 0, v152
	v_add_f32_e32 v91, 0, v153
	v_sub_f32_e32 v92, v96, v182
	v_add_f32_e32 v90, v156, v90
	v_add_f32_e32 v91, v157, v91
	v_exp_f32_e32 v169, v92
	v_add_f32_e32 v90, v160, v90
	v_add_f32_e32 v91, v161, v91
	v_sub_f32_e32 v92, v97, v182
	v_add_f32_e32 v90, v162, v90
	v_add_f32_e32 v91, v163, v91
	v_exp_f32_e32 v171, v92
	v_sub_f32_e32 v92, v98, v182
	v_add_f32_e32 v90, v164, v90
	v_add_f32_e32 v91, v165, v91
	v_exp_f32_e32 v173, v92
	v_sub_f32_e32 v92, v99, v182
	v_add_f32_e32 v90, v166, v90
	v_add_f32_e32 v91, v167, v91
	v_exp_f32_e32 v175, v92
	v_sub_f32_e32 v92, v100, v182
	v_exp_f32_e32 v177, v92
	v_sub_f32_e32 v92, v101, v182
	v_add_f32_e32 v90, v168, v90
	v_add_f32_e32 v91, v169, v91
	v_exp_f32_e32 v179, v92
	v_sub_f32_e32 v92, v102, v182
	v_add_f32_e32 v90, v170, v90
	v_add_f32_e32 v91, v171, v91
	v_exp_f32_e32 v181, v92
	v_sub_f32_e32 v92, v103, v182
	v_add_f32_e32 v90, v172, v90
	v_add_f32_e32 v91, v173, v91
	v_exp_f32_e32 v193, v92
	v_sub_f32_e32 v92, v104, v182
	v_add_f32_e32 v90, v174, v90
	v_add_f32_e32 v91, v175, v91
	v_sub_f32_e32 v127, v127, v182
	v_exp_f32_e32 v195, v92
	v_sub_f32_e32 v92, v105, v182
	v_add_f32_e32 v90, v176, v90
	v_add_f32_e32 v91, v177, v91
	v_exp_f32_e32 v159, v127
	v_exp_f32_e32 v197, v92
	v_add_f32_e32 v90, v178, v90
	v_add_f32_e32 v91, v179, v91
	v_cvt_pk_bf16_f32 v78, v172, v174
	v_add_f32_e32 v90, v180, v90
	v_add_f32_e32 v91, v181, v91
	v_mov_b32_e32 v98, v159
	v_add_f32_e32 v90, v192, v90
	v_add_f32_e32 v91, v193, v91
	v_mul_f32_e32 v92, v52, v98
	v_mul_f32_e32 v93, v53, v98
	v_add_f32_e32 v90, v194, v90
	v_add_f32_e32 v91, v195, v91
	v_mul_f32_e32 v96, v56, v98
	v_mul_f32_e32 v97, v57, v98
	v_add_f32_e32 v90, v196, v90
	v_add_f32_e32 v91, v197, v91
	v_mul_f32_e32 v94, v54, v98
	v_mul_f32_e32 v95, v55, v98
	v_pk_fma_f32 v[150:151], v[150:151], v[158:159], v[90:91]
	v_mul_f32_e32 v90, v50, v98
	v_mul_f32_e32 v91, v51, v98
	v_mul_f32_e32 v60, v60, v98
	v_mul_f32_e32 v61, v61, v98
	v_mul_f32_e32 v58, v58, v98
	v_mul_f32_e32 v59, v59, v98
	v_mul_f32_e32 v52, v64, v98
	v_mul_f32_e32 v53, v65, v98
	v_mul_f32_e32 v50, v62, v98
	v_mul_f32_e32 v51, v63, v98
	v_lshlrev_b32_e32 v98, 1, v187
	v_add3_u32 v127, s18, v98, v189
	ds_read_b64_tr_b16 v[100:101], v127 offset:15872
	ds_read_b64_tr_b16 v[98:99], v127 offset:13312
	ds_read_b64_tr_b16 v[102:103], v127 offset:13320
	v_cvt_pk_bf16_f32 v54, v153, v157
	v_cvt_pk_bf16_f32 v55, v161, v163
	v_cvt_pk_bf16_f32 v56, v165, v167
	v_cvt_pk_bf16_f32 v57, v169, v171
	s_waitcnt lgkmcnt(1)
	v_mfma_f32_16x16x32_bf16 v[82:85], v[98:101], v[70:73], v[82:85]
	ds_read_b64_tr_b16 v[104:105], v127 offset:15880
	v_cvt_pk_bf16_f32 v79, v176, v178
	v_cvt_pk_bf16_f32 v80, v180, v192
	v_mfma_f32_16x16x32_bf16 v[90:93], v[98:101], v[54:57], v[90:93]
	ds_read_b64_tr_b16 v[98:99], v127 offset:13376
	ds_read_b64_tr_b16 v[100:101], v127 offset:15936
	v_cvt_pk_bf16_f32 v81, v194, v196
	v_cvt_pk_bf16_f32 v62, v173, v175
	s_waitcnt lgkmcnt(0)
	v_mfma_f32_16x16x32_bf16 v[74:77], v[98:101], v[70:73], v[74:77]
	v_cvt_pk_bf16_f32 v63, v177, v179
	v_cvt_pk_bf16_f32 v64, v181, v193
	v_cvt_pk_bf16_f32 v65, v195, v197
	v_mfma_f32_16x16x32_bf16 v[58:61], v[98:101], v[54:57], v[58:61]
	ds_read_b64_tr_b16 v[98:99], v127 offset:13384
	ds_read_b64_tr_b16 v[100:101], v127 offset:15944
	v_mfma_f32_16x16x32_bf16 v[86:89], v[102:105], v[70:73], v[86:89]
	v_mfma_f32_16x16x32_bf16 v[94:97], v[102:105], v[54:57], v[94:97]
	s_waitcnt lgkmcnt(0)
	v_mfma_f32_16x16x32_bf16 v[102:105], v[98:101], v[70:73], v[66:69]
	v_mfma_f32_16x16x32_bf16 v[98:101], v[98:101], v[54:57], v[50:53]
	s_nop 2
	ds_read_b64_tr_b16 v[50:51], v127 offset:18432
	ds_read_b64_tr_b16 v[52:53], v127 offset:20992
	ds_read_b64_tr_b16 v[54:55], v127 offset:18440
	ds_read_b64_tr_b16 v[56:57], v127 offset:21000
	s_waitcnt lgkmcnt(2)
	v_mfma_f32_16x16x32_bf16 v[66:69], v[50:53], v[78:81], v[82:85]
	s_nop 2
	ds_read_b64_tr_b16 v[82:83], v127 offset:18496
	ds_read_b64_tr_b16 v[84:85], v127 offset:21056
	s_waitcnt lgkmcnt(0)
	v_mfma_f32_16x16x32_bf16 v[74:77], v[82:85], v[78:81], v[74:77]
	v_mfma_f32_16x16x32_bf16 v[58:61], v[82:85], v[62:65], v[58:61]
	ds_read_b64_tr_b16 v[82:83], v127 offset:18504
	ds_read_b64_tr_b16 v[84:85], v127 offset:21064
	v_mov_b32_e32 v127, v182
	v_mfma_f32_16x16x32_bf16 v[50:53], v[50:53], v[62:65], v[90:93]
	v_mfma_f32_16x16x32_bf16 v[70:73], v[54:57], v[78:81], v[86:89]
	v_mfma_f32_16x16x32_bf16 v[54:57], v[54:57], v[62:65], v[94:97]
	s_waitcnt lgkmcnt(0)
	v_mfma_f32_16x16x32_bf16 v[78:81], v[82:85], v[78:81], v[102:105]
	v_mfma_f32_16x16x32_bf16 v[62:65], v[82:85], v[62:65], v[98:101]
	v_mov_b32_e32 v82, v143
	s_branch .LBB0_1042

.LBB0_1077:
	v_add3_u32 v83, s18, v186, v188
	ds_read_b128 v[84:87], v83
	ds_read_b128 v[92:95], v83 offset:64
	s_waitcnt lgkmcnt(1)
	v_mfma_f32_16x16x32_bf16 v[88:91], v[84:87], v[8:11], 0
	ds_read_b128 v[98:101], v83 offset:3392
	ds_read_b128 v[102:105], v83 offset:6720
	ds_read_b128 v[144:147], v83 offset:10048
	v_mfma_f32_16x16x32_bf16 v[84:87], v[84:87], v[12:15], 0
	s_waitcnt lgkmcnt(3)
	v_mfma_f32_16x16x32_bf16 v[88:91], v[92:95], v[0:3], v[88:91]
	v_mfma_f32_16x16x32_bf16 v[84:87], v[92:95], v[16:19], v[84:87]
	ds_read_b128 v[92:95], v83 offset:128
	s_waitcnt lgkmcnt(0)
	v_mfma_f32_16x16x32_bf16 v[150:153], v[92:95], v[4:7], v[88:91]
	v_mfma_f32_16x16x32_bf16 v[90:93], v[92:95], v[20:23], v[84:87]
	s_nop 3
	ds_read_b128 v[84:87], v83 offset:3328
	s_waitcnt lgkmcnt(0)
	v_mfma_f32_16x16x32_bf16 v[94:97], v[84:87], v[8:11], 0
	v_mfma_f32_16x16x32_bf16 v[84:87], v[84:87], v[12:15], 0
	v_mfma_f32_16x16x32_bf16 v[94:97], v[98:101], v[0:3], v[94:97]
	v_mfma_f32_16x16x32_bf16 v[84:87], v[98:101], v[16:19], v[84:87]
	ds_read_b128 v[98:101], v83 offset:3456
	s_waitcnt lgkmcnt(0)
	v_mfma_f32_16x16x32_bf16 v[158:161], v[98:101], v[4:7], v[94:97]
	v_mfma_f32_16x16x32_bf16 v[94:97], v[98:101], v[20:23], v[84:87]
	s_nop 3
	ds_read_b128 v[84:87], v83 offset:6656
	s_waitcnt lgkmcnt(0)
	v_mfma_f32_16x16x32_bf16 v[98:101], v[84:87], v[8:11], 0
	v_mfma_f32_16x16x32_bf16 v[84:87], v[84:87], v[12:15], 0
	v_mfma_f32_16x16x32_bf16 v[98:101], v[102:105], v[0:3], v[98:101]
	v_mfma_f32_16x16x32_bf16 v[84:87], v[102:105], v[16:19], v[84:87]
	ds_read_b128 v[102:105], v83 offset:6784
	s_waitcnt lgkmcnt(0)
	v_mfma_f32_16x16x32_bf16 v[166:169], v[102:105], v[4:7], v[98:101]
	v_mfma_f32_16x16x32_bf16 v[98:101], v[102:105], v[20:23], v[84:87]
	s_nop 3
	ds_read_b128 v[84:87], v83 offset:9984
	s_waitcnt lgkmcnt(0)
	v_mfma_f32_16x16x32_bf16 v[102:105], v[84:87], v[8:11], 0
	v_mfma_f32_16x16x32_bf16 v[84:87], v[84:87], v[12:15], 0
	v_mfma_f32_16x16x32_bf16 v[102:105], v[144:147], v[0:3], v[102:105]
	v_mfma_f32_16x16x32_bf16 v[84:87], v[144:147], v[16:19], v[84:87]
	ds_read_b128 v[144:147], v83 offset:10112
	s_waitcnt lgkmcnt(0)
	v_mfma_f32_16x16x32_bf16 v[178:181], v[144:147], v[4:7], v[102:105]
	v_mfma_f32_16x16x32_bf16 v[102:105], v[144:147], v[20:23], v[84:87]
	s_nop 1
	v_max_f32_e32 v83, v150, v151
	s_nop 0
	v_max_f32_e32 v84, v152, v153
	v_max_f32_e32 v85, v160, v161
	v_max3_f32 v85, v158, v159, v85
	v_max3_f32 v83, v83, v84, v85
	v_max_f32_e32 v84, v168, v169
	v_max_f32_e32 v86, v180, v180
	v_max_f32_e32 v85, v86, v181
	v_max3_f32 v84, v166, v167, v84
	v_max3_f32 v85, v178, v179, v85
	v_max3_f32 v83, v83, v84, v85
	s_waitcnt lgkmcnt(0)
	v_mov_b32_e32 v84, v83
	s_nop 1
	v_permlane16_swap_b32_e32 v83, v84
	v_max_f32_e32 v83, v83, v84
	v_mov_b32_e32 v84, v83
	s_nop 1
	v_permlane32_swap_b32_e32 v83, v84
	v_max3_f32 v176, v82, v83, v84
	v_sub_f32_e32 v82, v82, v176
	v_exp_f32_e32 v146, v82
	v_sub_f32_e32 v82, v150, v176
	v_exp_f32_e32 v142, v82
	v_sub_f32_e32 v82, v151, v176
	v_exp_f32_e32 v144, v82
	v_sub_f32_e32 v82, v152, v176
	v_exp_f32_e32 v150, v82
	v_sub_f32_e32 v82, v153, v176
	v_exp_f32_e32 v152, v82
	v_sub_f32_e32 v82, v158, v176
	v_exp_f32_e32 v156, v82
	v_sub_f32_e32 v82, v159, v176
	v_exp_f32_e32 v158, v82
	v_sub_f32_e32 v82, v160, v176
	v_exp_f32_e32 v160, v82
	v_sub_f32_e32 v82, v161, v176
	v_exp_f32_e32 v162, v82
	v_sub_f32_e32 v82, v166, v176
	v_exp_f32_e32 v164, v82
	v_sub_f32_e32 v82, v167, v176
	v_exp_f32_e32 v166, v82
	v_sub_f32_e32 v82, v168, v176
	v_exp_f32_e32 v168, v82
	v_sub_f32_e32 v82, v169, v176
	v_exp_f32_e32 v170, v82
	v_sub_f32_e32 v82, v178, v176
	v_exp_f32_e32 v172, v82
	v_sub_f32_e32 v82, v179, v176
	v_exp_f32_e32 v174, v82
	v_sub_f32_e32 v82, v180, v176
	v_exp_f32_e32 v178, v82
	v_sub_f32_e32 v82, v181, v176
	v_exp_f32_e32 v180, v82
	v_mul_f32_e32 v84, v68, v146
	v_mul_f32_e32 v85, v69, v146
	v_mul_f32_e32 v82, v66, v146
	v_mul_f32_e32 v83, v67, v146
	v_mul_f32_e32 v88, v72, v146
	v_mul_f32_e32 v89, v73, v146
	v_mul_f32_e32 v86, v70, v146
	v_mul_f32_e32 v87, v71, v146
	v_mul_f32_e32 v76, v76, v146
	v_mul_f32_e32 v77, v77, v146
	v_mul_f32_e32 v74, v74, v146
	v_mul_f32_e32 v75, v75, v146
	v_mul_f32_e32 v68, v80, v146
	v_mul_f32_e32 v69, v81, v146
	v_mul_f32_e32 v66, v78, v146
	v_mul_f32_e32 v67, v79, v146
	v_max_f32_e32 v145, v90, v91
	v_max_f32_e32 v147, v92, v93
	v_max_f32_e32 v151, v96, v97
	v_max3_f32 v151, v94, v95, v151
	v_max3_f32 v145, v145, v147, v151
	v_max_f32_e32 v147, v100, v101
	v_max_f32_e32 v151, v104, v105
	v_max3_f32 v147, v98, v99, v147
	v_max3_f32 v151, v102, v103, v151
	v_max3_f32 v145, v145, v147, v151
	v_cvt_pk_bf16_f32 v70, v142, v144
	v_cvt_pk_bf16_f32 v71, v150, v152
	v_cvt_pk_bf16_f32 v72, v156, v158
	v_cvt_pk_bf16_f32 v73, v160, v162
	s_waitcnt lgkmcnt(0)
	v_mov_b32_e32 v147, v145
	s_nop 1
	v_permlane16_swap_b32_e32 v145, v147
	v_max_f32_e32 v145, v145, v147
	v_mov_b32_e32 v147, v145
	s_nop 1
	v_permlane32_swap_b32_e32 v145, v147
	v_max3_f32 v177, v143, v145, v147
	v_sub_f32_e32 v143, v143, v177
	v_sub_f32_e32 v90, v90, v177
	v_exp_f32_e32 v147, v143
	v_exp_f32_e32 v143, v90
	v_sub_f32_e32 v90, v91, v177
	v_exp_f32_e32 v145, v90
	v_sub_f32_e32 v90, v92, v177
	v_exp_f32_e32 v151, v90
	v_sub_f32_e32 v90, v93, v177
	v_exp_f32_e32 v153, v90
	v_sub_f32_e32 v90, v94, v177
	v_exp_f32_e32 v157, v90
	v_sub_f32_e32 v90, v95, v177
	v_exp_f32_e32 v159, v90
	v_add_f32_e32 v90, 0, v142
	v_add_f32_e32 v91, 0, v143
	v_sub_f32_e32 v92, v96, v177
	v_add_f32_e32 v90, v144, v90
	v_add_f32_e32 v91, v145, v91
	v_exp_f32_e32 v161, v92
	v_add_f32_e32 v90, v150, v90
	v_add_f32_e32 v91, v151, v91
	v_sub_f32_e32 v92, v97, v177
	v_add_f32_e32 v90, v152, v90
	v_add_f32_e32 v91, v153, v91
	v_exp_f32_e32 v163, v92
	v_sub_f32_e32 v92, v98, v177
	v_add_f32_e32 v90, v156, v90
	v_add_f32_e32 v91, v157, v91
	v_exp_f32_e32 v165, v92
	v_sub_f32_e32 v92, v99, v177
	v_add_f32_e32 v90, v158, v90
	v_add_f32_e32 v91, v159, v91
	v_exp_f32_e32 v167, v92
	v_sub_f32_e32 v92, v100, v177
	v_exp_f32_e32 v169, v92
	v_sub_f32_e32 v92, v101, v177
	v_add_f32_e32 v90, v160, v90
	v_add_f32_e32 v91, v161, v91
	v_exp_f32_e32 v171, v92
	v_sub_f32_e32 v92, v102, v177
	v_add_f32_e32 v90, v162, v90
	v_add_f32_e32 v91, v163, v91
	v_exp_f32_e32 v173, v92
	v_sub_f32_e32 v92, v103, v177
	v_add_f32_e32 v90, v164, v90
	v_add_f32_e32 v91, v165, v91
	v_exp_f32_e32 v175, v92
	v_sub_f32_e32 v92, v104, v177
	v_add_f32_e32 v90, v166, v90
	v_add_f32_e32 v91, v167, v91
	v_exp_f32_e32 v179, v92
	v_sub_f32_e32 v92, v105, v177
	v_add_f32_e32 v90, v168, v90
	v_add_f32_e32 v91, v169, v91
	v_exp_f32_e32 v181, v92
	v_add_f32_e32 v90, v170, v90
	v_add_f32_e32 v91, v171, v91
	v_mov_b32_e32 v98, v147
	v_add_f32_e32 v90, v172, v90
	v_add_f32_e32 v91, v173, v91
	v_add3_u32 v142, s18, v127, v189
	v_add_f32_e32 v90, v174, v90
	v_add_f32_e32 v91, v175, v91
	v_mul_f32_e32 v92, v52, v98
	v_mul_f32_e32 v93, v53, v98
	v_add_f32_e32 v90, v178, v90
	v_add_f32_e32 v91, v179, v91
	v_mul_f32_e32 v96, v56, v98
	v_mul_f32_e32 v97, v57, v98
	v_add_f32_e32 v90, v180, v90
	v_add_f32_e32 v91, v181, v91
	v_mul_f32_e32 v94, v54, v98
	v_mul_f32_e32 v95, v55, v98
	v_pk_fma_f32 v[140:141], v[140:141], v[146:147], v[90:91]
	v_mul_f32_e32 v90, v50, v98
	v_mul_f32_e32 v91, v51, v98
	v_mul_f32_e32 v60, v60, v98
	v_mul_f32_e32 v61, v61, v98
	v_mul_f32_e32 v58, v58, v98
	v_mul_f32_e32 v59, v59, v98
	v_mul_f32_e32 v52, v64, v98
	v_mul_f32_e32 v53, v65, v98
	v_mul_f32_e32 v50, v62, v98
	v_mul_f32_e32 v51, v63, v98
	ds_read_b64_tr_b16 v[100:101], v142 offset:15872
	ds_read_b64_tr_b16 v[98:99], v142 offset:13312
	ds_read_b64_tr_b16 v[102:103], v142 offset:13320
	v_cvt_pk_bf16_f32 v54, v143, v145
	v_cvt_pk_bf16_f32 v55, v151, v153
	v_cvt_pk_bf16_f32 v56, v157, v159
	v_cvt_pk_bf16_f32 v57, v161, v163
	s_waitcnt lgkmcnt(1)
	v_mfma_f32_16x16x32_bf16 v[82:85], v[98:101], v[70:73], v[82:85]
	ds_read_b64_tr_b16 v[104:105], v142 offset:15880
	v_cvt_pk_bf16_f32 v78, v164, v166
	v_cvt_pk_bf16_f32 v79, v168, v170
	v_mfma_f32_16x16x32_bf16 v[90:93], v[98:101], v[54:57], v[90:93]
	ds_read_b64_tr_b16 v[98:99], v142 offset:13376
	ds_read_b64_tr_b16 v[100:101], v142 offset:15936
	v_cvt_pk_bf16_f32 v80, v172, v174
	v_cvt_pk_bf16_f32 v81, v178, v180
	s_waitcnt lgkmcnt(0)
	v_mfma_f32_16x16x32_bf16 v[74:77], v[98:101], v[70:73], v[74:77]
	v_cvt_pk_bf16_f32 v62, v165, v167
	v_cvt_pk_bf16_f32 v63, v169, v171
	v_cvt_pk_bf16_f32 v64, v173, v175
	v_mfma_f32_16x16x32_bf16 v[58:61], v[98:101], v[54:57], v[58:61]
	ds_read_b64_tr_b16 v[98:99], v142 offset:13384
	ds_read_b64_tr_b16 v[100:101], v142 offset:15944
	v_cvt_pk_bf16_f32 v65, v179, v181
	v_mov_b32_e32 v143, v177
	v_mfma_f32_16x16x32_bf16 v[86:89], v[102:105], v[70:73], v[86:89]
	v_mfma_f32_16x16x32_bf16 v[94:97], v[102:105], v[54:57], v[94:97]
	s_waitcnt lgkmcnt(0)
	v_mfma_f32_16x16x32_bf16 v[102:105], v[98:101], v[70:73], v[66:69]
	v_mfma_f32_16x16x32_bf16 v[98:101], v[98:101], v[54:57], v[50:53]
	s_nop 2
	ds_read_b64_tr_b16 v[50:51], v142 offset:18432
	ds_read_b64_tr_b16 v[52:53], v142 offset:20992
	ds_read_b64_tr_b16 v[54:55], v142 offset:18440
	ds_read_b64_tr_b16 v[56:57], v142 offset:21000
	s_waitcnt lgkmcnt(2)
	v_mfma_f32_16x16x32_bf16 v[66:69], v[50:53], v[78:81], v[82:85]
	s_nop 2
	ds_read_b64_tr_b16 v[82:83], v142 offset:18496
	ds_read_b64_tr_b16 v[84:85], v142 offset:21056
	s_waitcnt lgkmcnt(0)
	v_mfma_f32_16x16x32_bf16 v[74:77], v[82:85], v[78:81], v[74:77]
	v_mfma_f32_16x16x32_bf16 v[58:61], v[82:85], v[62:65], v[58:61]
	ds_read_b64_tr_b16 v[82:83], v142 offset:18504
	ds_read_b64_tr_b16 v[84:85], v142 offset:21064
	v_mfma_f32_16x16x32_bf16 v[50:53], v[50:53], v[62:65], v[90:93]
	v_mfma_f32_16x16x32_bf16 v[70:73], v[54:57], v[78:81], v[86:89]
	v_mfma_f32_16x16x32_bf16 v[54:57], v[54:57], v[62:65], v[94:97]
	s_waitcnt lgkmcnt(0)
	v_mfma_f32_16x16x32_bf16 v[78:81], v[82:85], v[78:81], v[102:105]
	v_mfma_f32_16x16x32_bf16 v[62:65], v[82:85], v[62:65], v[98:101]
	v_mov_b32_e32 v82, v176
	s_add_i32 s6, s46, -2
	s_cmp_ge_i32 s6, s52
	s_cbranch_scc1 .LBB0_1064
.LBB0_1078:
	s_and_b32 s6, s6, 3
	s_mulk_i32 s6, 0x5c00
	s_add_i32 s18, s6, 0
	v_add3_u32 v83, s18, v186, v188
	ds_read_b128 v[84:87], v83
	ds_read_b128 v[92:95], v83 offset:64
	v_add3_u32 v127, s18, v127, v189
	s_waitcnt lgkmcnt(1)
	v_mfma_f32_16x16x32_bf16 v[88:91], v[84:87], v[8:11], 0
	ds_read_b128 v[98:101], v83 offset:3392
	ds_read_b128 v[102:105], v83 offset:6720
	ds_read_b128 v[144:147], v83 offset:10048
	v_mfma_f32_16x16x32_bf16 v[84:87], v[84:87], v[12:15], 0
	s_waitcnt lgkmcnt(3)
	v_mfma_f32_16x16x32_bf16 v[88:91], v[92:95], v[0:3], v[88:91]
	v_mfma_f32_16x16x32_bf16 v[84:87], v[92:95], v[16:19], v[84:87]
	ds_read_b128 v[92:95], v83 offset:128
	s_waitcnt lgkmcnt(0)
	v_mfma_f32_16x16x32_bf16 v[150:153], v[92:95], v[4:7], v[88:91]
	v_mfma_f32_16x16x32_bf16 v[90:93], v[92:95], v[20:23], v[84:87]
	s_nop 3
	ds_read_b128 v[84:87], v83 offset:3328
	s_waitcnt lgkmcnt(0)
	v_mfma_f32_16x16x32_bf16 v[94:97], v[84:87], v[8:11], 0
	v_mfma_f32_16x16x32_bf16 v[84:87], v[84:87], v[12:15], 0
	v_mfma_f32_16x16x32_bf16 v[94:97], v[98:101], v[0:3], v[94:97]
	v_mfma_f32_16x16x32_bf16 v[84:87], v[98:101], v[16:19], v[84:87]
	ds_read_b128 v[98:101], v83 offset:3456
	s_waitcnt lgkmcnt(0)
	v_mfma_f32_16x16x32_bf16 v[158:161], v[98:101], v[4:7], v[94:97]
	v_mfma_f32_16x16x32_bf16 v[94:97], v[98:101], v[20:23], v[84:87]
	s_nop 3
	ds_read_b128 v[84:87], v83 offset:6656
	s_waitcnt lgkmcnt(0)
	v_mfma_f32_16x16x32_bf16 v[98:101], v[84:87], v[8:11], 0
	v_mfma_f32_16x16x32_bf16 v[84:87], v[84:87], v[12:15], 0
	v_mfma_f32_16x16x32_bf16 v[98:101], v[102:105], v[0:3], v[98:101]
	v_mfma_f32_16x16x32_bf16 v[84:87], v[102:105], v[16:19], v[84:87]
	ds_read_b128 v[102:105], v83 offset:6784
	s_waitcnt lgkmcnt(0)
	v_mfma_f32_16x16x32_bf16 v[166:169], v[102:105], v[4:7], v[98:101]
	v_mfma_f32_16x16x32_bf16 v[98:101], v[102:105], v[20:23], v[84:87]
	s_nop 3
	ds_read_b128 v[84:87], v83 offset:9984
	s_waitcnt lgkmcnt(0)
	v_mfma_f32_16x16x32_bf16 v[102:105], v[84:87], v[8:11], 0
	v_mfma_f32_16x16x32_bf16 v[84:87], v[84:87], v[12:15], 0
	v_mfma_f32_16x16x32_bf16 v[102:105], v[144:147], v[0:3], v[102:105]
	v_mfma_f32_16x16x32_bf16 v[84:87], v[144:147], v[16:19], v[84:87]
	ds_read_b128 v[144:147], v83 offset:10112
	s_waitcnt lgkmcnt(0)
	v_mfma_f32_16x16x32_bf16 v[176:179], v[144:147], v[4:7], v[102:105]
	v_mfma_f32_16x16x32_bf16 v[102:105], v[144:147], v[20:23], v[84:87]
	s_nop 1
	v_max_f32_e32 v83, v150, v151
	s_nop 0
	v_max_f32_e32 v84, v152, v153
	v_max_f32_e32 v85, v160, v161
	v_max3_f32 v85, v158, v159, v85
	v_max3_f32 v83, v83, v84, v85
	v_max_f32_e32 v84, v168, v169
	v_max_f32_e32 v86, v178, v178
	v_max_f32_e32 v85, v86, v179
	v_max3_f32 v84, v166, v167, v84
	v_max3_f32 v85, v176, v177, v85
	v_max3_f32 v83, v83, v84, v85
	s_waitcnt lgkmcnt(0)
	v_mov_b32_e32 v84, v83
	s_nop 1
	v_permlane16_swap_b32_e32 v83, v84
	v_max_f32_e32 v83, v83, v84
	v_mov_b32_e32 v84, v83
	s_nop 1
	v_permlane32_swap_b32_e32 v83, v84
	v_max3_f32 v174, v82, v83, v84
	v_sub_f32_e32 v82, v82, v174
	v_exp_f32_e32 v146, v82
	v_sub_f32_e32 v82, v150, v174
	v_exp_f32_e32 v142, v82
	v_sub_f32_e32 v82, v151, v174
	v_exp_f32_e32 v144, v82
	v_sub_f32_e32 v82, v152, v174
	v_exp_f32_e32 v150, v82
	v_sub_f32_e32 v82, v153, v174
	v_exp_f32_e32 v152, v82
	v_sub_f32_e32 v82, v158, v174
	v_exp_f32_e32 v156, v82
	v_sub_f32_e32 v82, v159, v174
	v_exp_f32_e32 v158, v82
	v_sub_f32_e32 v82, v160, v174
	v_exp_f32_e32 v160, v82
	v_sub_f32_e32 v82, v161, v174
	v_exp_f32_e32 v162, v82
	v_sub_f32_e32 v82, v166, v174
	v_exp_f32_e32 v164, v82
	v_sub_f32_e32 v82, v167, v174
	v_exp_f32_e32 v166, v82
	v_sub_f32_e32 v82, v168, v174
	v_exp_f32_e32 v168, v82
	v_sub_f32_e32 v82, v169, v174
	v_exp_f32_e32 v170, v82
	v_sub_f32_e32 v82, v176, v174
	v_exp_f32_e32 v172, v82
	v_sub_f32_e32 v82, v177, v174
	v_exp_f32_e32 v176, v82
	v_sub_f32_e32 v82, v178, v174
	v_exp_f32_e32 v178, v82
	v_sub_f32_e32 v82, v179, v174
	v_exp_f32_e32 v180, v82
	v_mul_f32_e32 v84, v68, v146
	v_mul_f32_e32 v85, v69, v146
	v_mul_f32_e32 v82, v66, v146
	v_mul_f32_e32 v83, v67, v146
	v_mul_f32_e32 v88, v72, v146
	v_mul_f32_e32 v89, v73, v146
	v_mul_f32_e32 v86, v70, v146
	v_mul_f32_e32 v87, v71, v146
	v_mul_f32_e32 v76, v76, v146
	v_mul_f32_e32 v77, v77, v146
	v_mul_f32_e32 v74, v74, v146
	v_mul_f32_e32 v75, v75, v146
	v_mul_f32_e32 v68, v80, v146
	v_mul_f32_e32 v69, v81, v146
	v_mul_f32_e32 v66, v78, v146
	v_mul_f32_e32 v67, v79, v146
	v_max_f32_e32 v145, v90, v91
	v_max_f32_e32 v147, v92, v93
	v_max_f32_e32 v151, v96, v97
	v_max3_f32 v151, v94, v95, v151
	v_max3_f32 v145, v145, v147, v151
	v_max_f32_e32 v147, v100, v101
	v_max_f32_e32 v151, v104, v105
	v_max3_f32 v147, v98, v99, v147
	v_max3_f32 v151, v102, v103, v151
	v_max3_f32 v145, v145, v147, v151
	v_cvt_pk_bf16_f32 v70, v142, v144
	v_cvt_pk_bf16_f32 v71, v150, v152
	v_cvt_pk_bf16_f32 v72, v156, v158
	v_cvt_pk_bf16_f32 v73, v160, v162
	s_waitcnt lgkmcnt(0)
	v_mov_b32_e32 v147, v145
	s_nop 1
	v_permlane16_swap_b32_e32 v145, v147
	v_max_f32_e32 v145, v145, v147
	v_mov_b32_e32 v147, v145
	s_nop 1
	v_permlane32_swap_b32_e32 v145, v147
	v_max3_f32 v175, v143, v145, v147
	v_sub_f32_e32 v143, v143, v175
	v_sub_f32_e32 v90, v90, v175
	v_exp_f32_e32 v147, v143
	v_exp_f32_e32 v143, v90
	v_sub_f32_e32 v90, v91, v175
	v_exp_f32_e32 v145, v90
	v_sub_f32_e32 v90, v92, v175
	v_exp_f32_e32 v151, v90
	v_sub_f32_e32 v90, v93, v175
	v_exp_f32_e32 v153, v90
	v_sub_f32_e32 v90, v94, v175
	v_exp_f32_e32 v157, v90
	v_sub_f32_e32 v90, v95, v175
	v_exp_f32_e32 v159, v90
	v_add_f32_e32 v90, 0, v142
	v_add_f32_e32 v91, 0, v143
	v_sub_f32_e32 v92, v96, v175
	v_add_f32_e32 v90, v144, v90
	v_add_f32_e32 v91, v145, v91
	v_exp_f32_e32 v161, v92
	v_add_f32_e32 v90, v150, v90
	v_add_f32_e32 v91, v151, v91
	v_sub_f32_e32 v92, v97, v175
	v_add_f32_e32 v90, v152, v90
	v_add_f32_e32 v91, v153, v91
	v_exp_f32_e32 v163, v92
	v_sub_f32_e32 v92, v98, v175
	v_add_f32_e32 v90, v156, v90
	v_add_f32_e32 v91, v157, v91
	v_exp_f32_e32 v165, v92
	v_sub_f32_e32 v92, v99, v175
	v_add_f32_e32 v90, v158, v90
	v_add_f32_e32 v91, v159, v91
	v_exp_f32_e32 v167, v92
	v_sub_f32_e32 v92, v100, v175
	v_exp_f32_e32 v169, v92
	v_sub_f32_e32 v92, v101, v175
	v_add_f32_e32 v90, v160, v90
	v_add_f32_e32 v91, v161, v91
	v_exp_f32_e32 v171, v92
	v_sub_f32_e32 v92, v102, v175
	v_add_f32_e32 v90, v162, v90
	v_add_f32_e32 v91, v163, v91
	v_exp_f32_e32 v173, v92
	v_sub_f32_e32 v92, v103, v175
	v_add_f32_e32 v90, v164, v90
	v_add_f32_e32 v91, v165, v91
	v_exp_f32_e32 v177, v92
	v_sub_f32_e32 v92, v104, v175
	v_add_f32_e32 v90, v166, v90
	v_add_f32_e32 v91, v167, v91
	v_exp_f32_e32 v179, v92
	v_sub_f32_e32 v92, v105, v175
	v_add_f32_e32 v90, v168, v90
	v_add_f32_e32 v91, v169, v91
	v_exp_f32_e32 v181, v92
	v_add_f32_e32 v90, v170, v90
	v_add_f32_e32 v91, v171, v91
	v_mov_b32_e32 v98, v147
	v_add_f32_e32 v90, v172, v90
	v_add_f32_e32 v91, v173, v91
	v_mul_f32_e32 v92, v52, v98
	v_mul_f32_e32 v93, v53, v98
	v_add_f32_e32 v90, v176, v90
	v_add_f32_e32 v91, v177, v91
	v_mul_f32_e32 v96, v56, v98
	v_mul_f32_e32 v97, v57, v98
	v_add_f32_e32 v90, v178, v90
	v_add_f32_e32 v91, v179, v91
	v_mul_f32_e32 v94, v54, v98
	v_mul_f32_e32 v95, v55, v98
	v_add_f32_e32 v90, v180, v90
	v_add_f32_e32 v91, v181, v91
	v_mul_f32_e32 v60, v60, v98
	v_mul_f32_e32 v61, v61, v98
	v_pk_fma_f32 v[140:141], v[140:141], v[146:147], v[90:91]
	v_mul_f32_e32 v90, v50, v98
	v_mul_f32_e32 v91, v51, v98
	v_mul_f32_e32 v58, v58, v98
	v_mul_f32_e32 v59, v59, v98
	v_mul_f32_e32 v52, v64, v98
	v_mul_f32_e32 v53, v65, v98
	v_mul_f32_e32 v50, v62, v98
	v_mul_f32_e32 v51, v63, v98
	ds_read_b64_tr_b16 v[100:101], v127 offset:15872
	ds_read_b64_tr_b16 v[98:99], v127 offset:13312
	ds_read_b64_tr_b16 v[102:103], v127 offset:13320
	v_cvt_pk_bf16_f32 v54, v143, v145
	v_cvt_pk_bf16_f32 v55, v151, v153
	v_cvt_pk_bf16_f32 v56, v157, v159
	v_cvt_pk_bf16_f32 v57, v161, v163
	s_waitcnt lgkmcnt(1)
	v_mfma_f32_16x16x32_bf16 v[82:85], v[98:101], v[70:73], v[82:85]
	ds_read_b64_tr_b16 v[104:105], v127 offset:15880
	v_cvt_pk_bf16_f32 v78, v164, v166
	v_cvt_pk_bf16_f32 v79, v168, v170
	v_mfma_f32_16x16x32_bf16 v[90:93], v[98:101], v[54:57], v[90:93]
	ds_read_b64_tr_b16 v[98:99], v127 offset:13376
	ds_read_b64_tr_b16 v[100:101], v127 offset:15936
	v_cvt_pk_bf16_f32 v80, v172, v176
	v_cvt_pk_bf16_f32 v81, v178, v180
	s_waitcnt lgkmcnt(0)
	v_mfma_f32_16x16x32_bf16 v[74:77], v[98:101], v[70:73], v[74:77]
	v_cvt_pk_bf16_f32 v62, v165, v167
	v_cvt_pk_bf16_f32 v63, v169, v171
	v_cvt_pk_bf16_f32 v64, v173, v177
	v_mfma_f32_16x16x32_bf16 v[58:61], v[98:101], v[54:57], v[58:61]
	ds_read_b64_tr_b16 v[98:99], v127 offset:13384
	ds_read_b64_tr_b16 v[100:101], v127 offset:15944
	v_cvt_pk_bf16_f32 v65, v179, v181
	v_mov_b32_e32 v143, v175
	v_mfma_f32_16x16x32_bf16 v[86:89], v[102:105], v[70:73], v[86:89]
	v_mfma_f32_16x16x32_bf16 v[94:97], v[102:105], v[54:57], v[94:97]
	s_waitcnt lgkmcnt(0)
	v_mfma_f32_16x16x32_bf16 v[102:105], v[98:101], v[70:73], v[66:69]
	v_mfma_f32_16x16x32_bf16 v[98:101], v[98:101], v[54:57], v[50:53]
	s_nop 2
	ds_read_b64_tr_b16 v[50:51], v127 offset:18432
	ds_read_b64_tr_b16 v[52:53], v127 offset:20992
	ds_read_b64_tr_b16 v[54:55], v127 offset:18440
	ds_read_b64_tr_b16 v[56:57], v127 offset:21000
	s_waitcnt lgkmcnt(2)
	v_mfma_f32_16x16x32_bf16 v[66:69], v[50:53], v[78:81], v[82:85]
	s_nop 2
	ds_read_b64_tr_b16 v[82:83], v127 offset:18496
	ds_read_b64_tr_b16 v[84:85], v127 offset:21056
	s_waitcnt lgkmcnt(0)
	v_mfma_f32_16x16x32_bf16 v[74:77], v[82:85], v[78:81], v[74:77]
	v_mfma_f32_16x16x32_bf16 v[58:61], v[82:85], v[62:65], v[58:61]
	ds_read_b64_tr_b16 v[82:83], v127 offset:18504
	ds_read_b64_tr_b16 v[84:85], v127 offset:21064
	v_mfma_f32_16x16x32_bf16 v[50:53], v[50:53], v[62:65], v[90:93]
	v_mfma_f32_16x16x32_bf16 v[70:73], v[54:57], v[78:81], v[86:89]
	v_mfma_f32_16x16x32_bf16 v[54:57], v[54:57], v[62:65], v[94:97]
	s_waitcnt lgkmcnt(0)
	v_mfma_f32_16x16x32_bf16 v[78:81], v[82:85], v[78:81], v[102:105]
	v_mfma_f32_16x16x32_bf16 v[62:65], v[82:85], v[62:65], v[98:101]
	v_mov_b32_e32 v82, v174
	s_branch .LBB0_1064
